# hand-written final RMSNorm phase (all row loads batched, norm_f loaded once per wave) + batched generic sample-unit K loop for the pooling GEMM
# speedup vs baseline: 1.0051x; 1.0051x over previous
.LBB0_41:
	s_mov_b64 s[48:49], s[78:79]
	s_cmp_lt_i32 s54, 2
	s_mov_b64 s[0:1], -1
	s_cbranch_scc1 .LBB0_460
	s_cmp_lt_i32 s54, 6
	s_mov_b64 s[66:67], -1
	v_writelane_b32 v254, s54, 26
	s_cbranch_scc1 .LBB0_156
	s_cmp_gt_i32 s54, 6
	s_cbranch_scc0 .LBB0_50
	s_cmp_lg_u32 s54, 7
	s_cbranch_scc0 .LBB0_49
	s_load_dwordx2 s[4:5], s[78:79], 0xa0
	s_load_dwordx2 s[6:7], s[78:79], 0x98
	s_load_dwordx2 s[8:9], s[78:79], 0x90
	v_and_b32_e32 v2, 63, v170
	v_lshrrev_b32_e32 v3, 6, v170
	v_lshlrev_b32_e32 v4, 4, v2
	v_lshlrev_b32_e32 v5, 3, v2
	v_readfirstlane_b32 s32, v3
	v_add_u32_e32 v6, 0x1000, v4
	s_lshl_b32 s1, s76, 3
	s_add_u32 s32, s32, s1
	s_waitcnt vmcnt(0) lgkmcnt(0)
	s_add_u32 s12, s4, 0x73800
	s_addc_u32 s13, s5, 0
	s_add_u32 s10, s4, 0x13000000
	s_addc_u32 s11, s5, 0
	global_load_dwordx4 v[34:37], v4, s[8:9] offset:0
	global_load_dwordx4 v[38:41], v4, s[8:9] offset:1024
	global_load_dwordx4 v[42:45], v4, s[8:9] offset:2048
	global_load_dwordx4 v[46:49], v4, s[8:9] offset:3072
	global_load_dwordx4 v[50:53], v6, s[8:9] offset:0
	global_load_dwordx4 v[54:57], v6, s[8:9] offset:1024
	global_load_dwordx4 v[58:61], v6, s[8:9] offset:2048
	global_load_dwordx4 v[62:65], v6, s[8:9] offset:3072
	s_add_u32 s1, s32, 0
	s_lshl_b32 s1, s1, 3
	s_load_dwordx2 s[16:17], s[12:13], s1
	s_add_u32 s1, s32, 2048
	s_lshl_b32 s1, s1, 3
	s_load_dwordx2 s[98:99], s[12:13], s1
	s_add_u32 s1, s32, 4096
	s_lshl_b32 s1, s1, 3
	s_load_dwordx2 s[100:101], s[12:13], s1
	s_add_u32 s1, s32, 6144
	s_lshl_b32 s1, s1, 3
	s_load_dwordx2 s[14:15], s[12:13], s1
	s_cmp_lt_u32 s32, 0x100
	s_cbranch_scc0 .Lfn_q4skip
	s_add_u32 s1, s32, 8192
	s_lshl_b32 s1, s1, 3
	s_load_dwordx2 s[0:1], s[12:13], s1
.Lfn_q4skip:
	s_add_u32 vcc_lo, s32, 0
	s_mul_i32 vcc_lo, vcc_lo, 0x1080
	s_add_u32 s12, s10, vcc_lo
	s_addc_u32 s13, s11, 0
	global_load_dwordx2 v[66:67], v5, s[12:13] offset:0
	global_load_dwordx2 v[68:69], v5, s[12:13] offset:512
	global_load_dwordx2 v[70:71], v5, s[12:13] offset:1024
	global_load_dwordx2 v[72:73], v5, s[12:13] offset:1536
	global_load_dwordx2 v[74:75], v5, s[12:13] offset:2048
	global_load_dwordx2 v[76:77], v5, s[12:13] offset:2560
	global_load_dwordx2 v[78:79], v5, s[12:13] offset:3072
	global_load_dwordx2 v[80:81], v5, s[12:13] offset:3584
	s_add_u32 vcc_lo, s32, 2048
	s_mul_i32 vcc_lo, vcc_lo, 0x1080
	s_add_u32 s12, s10, vcc_lo
	s_addc_u32 s13, s11, 0
	global_load_dwordx2 v[82:83], v5, s[12:13] offset:0
	global_load_dwordx2 v[84:85], v5, s[12:13] offset:512
	global_load_dwordx2 v[86:87], v5, s[12:13] offset:1024
	global_load_dwordx2 v[88:89], v5, s[12:13] offset:1536
	global_load_dwordx2 v[90:91], v5, s[12:13] offset:2048
	global_load_dwordx2 v[92:93], v5, s[12:13] offset:2560
	global_load_dwordx2 v[94:95], v5, s[12:13] offset:3072
	global_load_dwordx2 v[96:97], v5, s[12:13] offset:3584
	s_add_u32 vcc_lo, s32, 4096
	s_mul_i32 vcc_lo, vcc_lo, 0x1080
	s_add_u32 s12, s10, vcc_lo
	s_addc_u32 s13, s11, 0
	global_load_dwordx2 v[98:99], v5, s[12:13] offset:0
	global_load_dwordx2 v[100:101], v5, s[12:13] offset:512
	global_load_dwordx2 v[102:103], v5, s[12:13] offset:1024
	global_load_dwordx2 v[104:105], v5, s[12:13] offset:1536
	global_load_dwordx2 v[106:107], v5, s[12:13] offset:2048
	global_load_dwordx2 v[108:109], v5, s[12:13] offset:2560
	global_load_dwordx2 v[110:111], v5, s[12:13] offset:3072
	global_load_dwordx2 v[112:113], v5, s[12:13] offset:3584
	s_add_u32 vcc_lo, s32, 6144
	s_mul_i32 vcc_lo, vcc_lo, 0x1080
	s_add_u32 s12, s10, vcc_lo
	s_addc_u32 s13, s11, 0
	global_load_dwordx2 v[114:115], v5, s[12:13] offset:0
	global_load_dwordx2 v[116:117], v5, s[12:13] offset:512
	global_load_dwordx2 v[118:119], v5, s[12:13] offset:1024
	global_load_dwordx2 v[120:121], v5, s[12:13] offset:1536
	global_load_dwordx2 v[122:123], v5, s[12:13] offset:2048
	global_load_dwordx2 v[124:125], v5, s[12:13] offset:2560
	global_load_dwordx2 v[126:127], v5, s[12:13] offset:3072
	global_load_dwordx2 v[128:129], v5, s[12:13] offset:3584
	s_cmp_lt_u32 s32, 0x100
	s_cbranch_scc0 .Lfn_h4skip
	s_add_u32 vcc_lo, s32, 8192
	s_mul_i32 vcc_lo, vcc_lo, 0x1080
	s_add_u32 s12, s10, vcc_lo
	s_addc_u32 s13, s11, 0
	global_load_dwordx2 v[142:143], v5, s[12:13] offset:0
	global_load_dwordx2 v[144:145], v5, s[12:13] offset:512
	global_load_dwordx2 v[146:147], v5, s[12:13] offset:1024
	global_load_dwordx2 v[148:149], v5, s[12:13] offset:1536
	global_load_dwordx2 v[150:151], v5, s[12:13] offset:2048
	global_load_dwordx2 v[152:153], v5, s[12:13] offset:2560
	global_load_dwordx2 v[154:155], v5, s[12:13] offset:3072
	global_load_dwordx2 v[156:157], v5, s[12:13] offset:3584
.Lfn_h4skip:
	s_waitcnt lgkmcnt(0)
	v_mov_b32_e32 v28, s16
	v_mov_b32_e32 v29, s17
	v_ffbh_u32_e32 v30, v29
	v_min_u32_e32 v30, 32, v30
	v_lshlrev_b64 v[28:29], v30, v[28:29]
	v_min_u32_e32 v28, 1, v28
	v_or_b32_e32 v28, v29, v28
	v_cvt_f32_u32_e32 v28, v28
	v_sub_u32_e32 v30, 32, v30
	v_ldexp_f32 v30, v28, v30
	v_mul_f32_e32 v30, 0x2f800000, v30
	v_fmamk_f32 v30, v30, 0x3a000000, v171
	v_mul_f32_e32 v28, 0x4f800000, v30
	v_cmp_gt_f32_e32 vcc, s51, v30
	s_nop 1
	v_cndmask_b32_e32 v30, v30, v28, vcc
	v_sqrt_f32_e32 v28, v30
	s_nop 0
	v_add_u32_e32 v29, -1, v28
	v_add_u32_e32 v31, 1, v28
	v_fma_f32 v32, -v29, v28, v30
	v_fma_f32 v33, -v31, v28, v30
	v_cmp_ge_f32_e64 s[10:11], 0, v32
	s_nop 1
	v_cndmask_b32_e64 v28, v28, v29, s[10:11]
	v_cmp_lt_f32_e64 s[10:11], 0, v33
	s_nop 1
	v_cndmask_b32_e64 v28, v28, v31, s[10:11]
	v_mul_f32_e32 v29, 0x37800000, v28
	v_cndmask_b32_e32 v28, v28, v29, vcc
	v_cmp_class_f32_e32 vcc, v30, v172
	s_nop 1
	v_cndmask_b32_e32 v30, v28, v30, vcc
	v_div_scale_f32 v28, s[10:11], v30, v30, 1.0
	v_rcp_f32_e32 v29, v28
	v_div_scale_f32 v31, vcc, 1.0, v30, 1.0
	v_fma_f32 v32, -v28, v29, 1.0
	v_fmac_f32_e32 v29, v32, v29
	v_mul_f32_e32 v32, v31, v29
	v_fma_f32 v33, -v28, v32, v31
	v_fmac_f32_e32 v32, v33, v29
	v_fma_f32 v28, -v28, v32, v31
	v_div_fmas_f32 v28, v28, v29, v32
	v_div_fixup_f32 v30, v28, v30, 1.0
	v_mov_b32_e32 v130, v30
	v_mov_b32_e32 v28, s98
	v_mov_b32_e32 v29, s99
	v_ffbh_u32_e32 v30, v29
	v_min_u32_e32 v30, 32, v30
	v_lshlrev_b64 v[28:29], v30, v[28:29]
	v_min_u32_e32 v28, 1, v28
	v_or_b32_e32 v28, v29, v28
	v_cvt_f32_u32_e32 v28, v28
	v_sub_u32_e32 v30, 32, v30
	v_ldexp_f32 v30, v28, v30
	v_mul_f32_e32 v30, 0x2f800000, v30
	v_fmamk_f32 v30, v30, 0x3a000000, v171
	v_mul_f32_e32 v28, 0x4f800000, v30
	v_cmp_gt_f32_e32 vcc, s51, v30
	s_nop 1
	v_cndmask_b32_e32 v30, v30, v28, vcc
	v_sqrt_f32_e32 v28, v30
	s_nop 0
	v_add_u32_e32 v29, -1, v28
	v_add_u32_e32 v31, 1, v28
	v_fma_f32 v32, -v29, v28, v30
	v_fma_f32 v33, -v31, v28, v30
	v_cmp_ge_f32_e64 s[10:11], 0, v32
	s_nop 1
	v_cndmask_b32_e64 v28, v28, v29, s[10:11]
	v_cmp_lt_f32_e64 s[10:11], 0, v33
	s_nop 1
	v_cndmask_b32_e64 v28, v28, v31, s[10:11]
	v_mul_f32_e32 v29, 0x37800000, v28
	v_cndmask_b32_e32 v28, v28, v29, vcc
	v_cmp_class_f32_e32 vcc, v30, v172
	s_nop 1
	v_cndmask_b32_e32 v30, v28, v30, vcc
	v_div_scale_f32 v28, s[10:11], v30, v30, 1.0
	v_rcp_f32_e32 v29, v28
	v_div_scale_f32 v31, vcc, 1.0, v30, 1.0
	v_fma_f32 v32, -v28, v29, 1.0
	v_fmac_f32_e32 v29, v32, v29
	v_mul_f32_e32 v32, v31, v29
	v_fma_f32 v33, -v28, v32, v31
	v_fmac_f32_e32 v32, v33, v29
	v_fma_f32 v28, -v28, v32, v31
	v_div_fmas_f32 v28, v28, v29, v32
	v_div_fixup_f32 v30, v28, v30, 1.0
	v_mov_b32_e32 v131, v30
	v_mov_b32_e32 v28, s100
	v_mov_b32_e32 v29, s101
	v_ffbh_u32_e32 v30, v29
	v_min_u32_e32 v30, 32, v30
	v_lshlrev_b64 v[28:29], v30, v[28:29]
	v_min_u32_e32 v28, 1, v28
	v_or_b32_e32 v28, v29, v28
	v_cvt_f32_u32_e32 v28, v28
	v_sub_u32_e32 v30, 32, v30
	v_ldexp_f32 v30, v28, v30
	v_mul_f32_e32 v30, 0x2f800000, v30
	v_fmamk_f32 v30, v30, 0x3a000000, v171
	v_mul_f32_e32 v28, 0x4f800000, v30
	v_cmp_gt_f32_e32 vcc, s51, v30
	s_nop 1
	v_cndmask_b32_e32 v30, v30, v28, vcc
	v_sqrt_f32_e32 v28, v30
	s_nop 0
	v_add_u32_e32 v29, -1, v28
	v_add_u32_e32 v31, 1, v28
	v_fma_f32 v32, -v29, v28, v30
	v_fma_f32 v33, -v31, v28, v30
	v_cmp_ge_f32_e64 s[10:11], 0, v32
	s_nop 1
	v_cndmask_b32_e64 v28, v28, v29, s[10:11]
	v_cmp_lt_f32_e64 s[10:11], 0, v33
	s_nop 1
	v_cndmask_b32_e64 v28, v28, v31, s[10:11]
	v_mul_f32_e32 v29, 0x37800000, v28
	v_cndmask_b32_e32 v28, v28, v29, vcc
	v_cmp_class_f32_e32 vcc, v30, v172
	s_nop 1
	v_cndmask_b32_e32 v30, v28, v30, vcc
	v_div_scale_f32 v28, s[10:11], v30, v30, 1.0
	v_rcp_f32_e32 v29, v28
	v_div_scale_f32 v31, vcc, 1.0, v30, 1.0
	v_fma_f32 v32, -v28, v29, 1.0
	v_fmac_f32_e32 v29, v32, v29
	v_mul_f32_e32 v32, v31, v29
	v_fma_f32 v33, -v28, v32, v31
	v_fmac_f32_e32 v32, v33, v29
	v_fma_f32 v28, -v28, v32, v31
	v_div_fmas_f32 v28, v28, v29, v32
	v_div_fixup_f32 v30, v28, v30, 1.0
	v_mov_b32_e32 v132, v30
	v_mov_b32_e32 v28, s14
	v_mov_b32_e32 v29, s15
	v_ffbh_u32_e32 v30, v29
	v_min_u32_e32 v30, 32, v30
	v_lshlrev_b64 v[28:29], v30, v[28:29]
	v_min_u32_e32 v28, 1, v28
	v_or_b32_e32 v28, v29, v28
	v_cvt_f32_u32_e32 v28, v28
	v_sub_u32_e32 v30, 32, v30
	v_ldexp_f32 v30, v28, v30
	v_mul_f32_e32 v30, 0x2f800000, v30
	v_fmamk_f32 v30, v30, 0x3a000000, v171
	v_mul_f32_e32 v28, 0x4f800000, v30
	v_cmp_gt_f32_e32 vcc, s51, v30
	s_nop 1
	v_cndmask_b32_e32 v30, v30, v28, vcc
	v_sqrt_f32_e32 v28, v30
	s_nop 0
	v_add_u32_e32 v29, -1, v28
	v_add_u32_e32 v31, 1, v28
	v_fma_f32 v32, -v29, v28, v30
	v_fma_f32 v33, -v31, v28, v30
	v_cmp_ge_f32_e64 s[10:11], 0, v32
	s_nop 1
	v_cndmask_b32_e64 v28, v28, v29, s[10:11]
	v_cmp_lt_f32_e64 s[10:11], 0, v33
	s_nop 1
	v_cndmask_b32_e64 v28, v28, v31, s[10:11]
	v_mul_f32_e32 v29, 0x37800000, v28
	v_cndmask_b32_e32 v28, v28, v29, vcc
	v_cmp_class_f32_e32 vcc, v30, v172
	s_nop 1
	v_cndmask_b32_e32 v30, v28, v30, vcc
	v_div_scale_f32 v28, s[10:11], v30, v30, 1.0
	v_rcp_f32_e32 v29, v28
	v_div_scale_f32 v31, vcc, 1.0, v30, 1.0
	v_fma_f32 v32, -v28, v29, 1.0
	v_fmac_f32_e32 v29, v32, v29
	v_mul_f32_e32 v32, v31, v29
	v_fma_f32 v33, -v28, v32, v31
	v_fmac_f32_e32 v32, v33, v29
	v_fma_f32 v28, -v28, v32, v31
	v_div_fmas_f32 v28, v28, v29, v32
	v_div_fixup_f32 v30, v28, v30, 1.0
	v_mov_b32_e32 v133, v30
	s_cmp_lt_u32 s32, 0x100
	s_cbranch_scc0 .Lfn_r4skip
	v_mov_b32_e32 v28, s0
	v_mov_b32_e32 v29, s1
	v_ffbh_u32_e32 v30, v29
	v_min_u32_e32 v30, 32, v30
	v_lshlrev_b64 v[28:29], v30, v[28:29]
	v_min_u32_e32 v28, 1, v28
	v_or_b32_e32 v28, v29, v28
	v_cvt_f32_u32_e32 v28, v28
	v_sub_u32_e32 v30, 32, v30
	v_ldexp_f32 v30, v28, v30
	v_mul_f32_e32 v30, 0x2f800000, v30
	v_fmamk_f32 v30, v30, 0x3a000000, v171
	v_mul_f32_e32 v28, 0x4f800000, v30
	v_cmp_gt_f32_e32 vcc, s51, v30
	s_nop 1
	v_cndmask_b32_e32 v30, v30, v28, vcc
	v_sqrt_f32_e32 v28, v30
	s_nop 0
	v_add_u32_e32 v29, -1, v28
	v_add_u32_e32 v31, 1, v28
	v_fma_f32 v32, -v29, v28, v30
	v_fma_f32 v33, -v31, v28, v30
	v_cmp_ge_f32_e64 s[10:11], 0, v32
	s_nop 1
	v_cndmask_b32_e64 v28, v28, v29, s[10:11]
	v_cmp_lt_f32_e64 s[10:11], 0, v33
	s_nop 1
	v_cndmask_b32_e64 v28, v28, v31, s[10:11]
	v_mul_f32_e32 v29, 0x37800000, v28
	v_cndmask_b32_e32 v28, v28, v29, vcc
	v_cmp_class_f32_e32 vcc, v30, v172
	s_nop 1
	v_cndmask_b32_e32 v30, v28, v30, vcc
	v_div_scale_f32 v28, s[10:11], v30, v30, 1.0
	v_rcp_f32_e32 v29, v28
	v_div_scale_f32 v31, vcc, 1.0, v30, 1.0
	v_fma_f32 v32, -v28, v29, 1.0
	v_fmac_f32_e32 v29, v32, v29
	v_mul_f32_e32 v32, v31, v29
	v_fma_f32 v33, -v28, v32, v31
	v_fmac_f32_e32 v32, v33, v29
	v_fma_f32 v28, -v28, v32, v31
	v_div_fmas_f32 v28, v28, v29, v32
	v_div_fixup_f32 v30, v28, v30, 1.0
	v_mov_b32_e32 v134, v30
.Lfn_r4skip:
	s_waitcnt vmcnt(0)
	s_add_u32 vcc_lo, s32, 0
	s_lshl_b32 vcc_lo, vcc_lo, 13
	s_add_u32 s12, s6, vcc_lo
	s_addc_u32 s13, s7, 0
	v_lshlrev_b32_e32 v10, 16, v66
	v_and_b32_e32 v11, 0xffff0000, v66
	v_lshlrev_b32_e32 v12, 16, v67
	v_and_b32_e32 v13, 0xffff0000, v67
	v_mul_f32_e32 v10, v130, v10
	v_mul_f32_e32 v11, v130, v11
	v_mul_f32_e32 v12, v130, v12
	v_mul_f32_e32 v13, v130, v13
	v_pk_mul_f32 v[10:11], v[10:11], v[34:35]
	v_pk_mul_f32 v[12:13], v[12:13], v[36:37]
	global_store_dwordx4 v4, v[10:13], s[12:13] offset:0
	v_lshlrev_b32_e32 v14, 16, v68
	v_and_b32_e32 v15, 0xffff0000, v68
	v_lshlrev_b32_e32 v16, 16, v69
	v_and_b32_e32 v17, 0xffff0000, v69
	v_mul_f32_e32 v14, v130, v14
	v_mul_f32_e32 v15, v130, v15
	v_mul_f32_e32 v16, v130, v16
	v_mul_f32_e32 v17, v130, v17
	v_pk_mul_f32 v[14:15], v[14:15], v[38:39]
	v_pk_mul_f32 v[16:17], v[16:17], v[40:41]
	global_store_dwordx4 v4, v[14:17], s[12:13] offset:1024
	v_lshlrev_b32_e32 v10, 16, v70
	v_and_b32_e32 v11, 0xffff0000, v70
	v_lshlrev_b32_e32 v12, 16, v71
	v_and_b32_e32 v13, 0xffff0000, v71
	v_mul_f32_e32 v10, v130, v10
	v_mul_f32_e32 v11, v130, v11
	v_mul_f32_e32 v12, v130, v12
	v_mul_f32_e32 v13, v130, v13
	v_pk_mul_f32 v[10:11], v[10:11], v[42:43]
	v_pk_mul_f32 v[12:13], v[12:13], v[44:45]
	global_store_dwordx4 v4, v[10:13], s[12:13] offset:2048
	v_lshlrev_b32_e32 v14, 16, v72
	v_and_b32_e32 v15, 0xffff0000, v72
	v_lshlrev_b32_e32 v16, 16, v73
	v_and_b32_e32 v17, 0xffff0000, v73
	v_mul_f32_e32 v14, v130, v14
	v_mul_f32_e32 v15, v130, v15
	v_mul_f32_e32 v16, v130, v16
	v_mul_f32_e32 v17, v130, v17
	v_pk_mul_f32 v[14:15], v[14:15], v[46:47]
	v_pk_mul_f32 v[16:17], v[16:17], v[48:49]
	global_store_dwordx4 v4, v[14:17], s[12:13] offset:3072
	v_lshlrev_b32_e32 v10, 16, v74
	v_and_b32_e32 v11, 0xffff0000, v74
	v_lshlrev_b32_e32 v12, 16, v75
	v_and_b32_e32 v13, 0xffff0000, v75
	v_mul_f32_e32 v10, v130, v10
	v_mul_f32_e32 v11, v130, v11
	v_mul_f32_e32 v12, v130, v12
	v_mul_f32_e32 v13, v130, v13
	v_pk_mul_f32 v[10:11], v[10:11], v[50:51]
	v_pk_mul_f32 v[12:13], v[12:13], v[52:53]
	global_store_dwordx4 v6, v[10:13], s[12:13] offset:0
	v_lshlrev_b32_e32 v14, 16, v76
	v_and_b32_e32 v15, 0xffff0000, v76
	v_lshlrev_b32_e32 v16, 16, v77
	v_and_b32_e32 v17, 0xffff0000, v77
	v_mul_f32_e32 v14, v130, v14
	v_mul_f32_e32 v15, v130, v15
	v_mul_f32_e32 v16, v130, v16
	v_mul_f32_e32 v17, v130, v17
	v_pk_mul_f32 v[14:15], v[14:15], v[54:55]
	v_pk_mul_f32 v[16:17], v[16:17], v[56:57]
	global_store_dwordx4 v6, v[14:17], s[12:13] offset:1024
	v_lshlrev_b32_e32 v10, 16, v78
	v_and_b32_e32 v11, 0xffff0000, v78
	v_lshlrev_b32_e32 v12, 16, v79
	v_and_b32_e32 v13, 0xffff0000, v79
	v_mul_f32_e32 v10, v130, v10
	v_mul_f32_e32 v11, v130, v11
	v_mul_f32_e32 v12, v130, v12
	v_mul_f32_e32 v13, v130, v13
	v_pk_mul_f32 v[10:11], v[10:11], v[58:59]
	v_pk_mul_f32 v[12:13], v[12:13], v[60:61]
	global_store_dwordx4 v6, v[10:13], s[12:13] offset:2048
	v_lshlrev_b32_e32 v14, 16, v80
	v_and_b32_e32 v15, 0xffff0000, v80
	v_lshlrev_b32_e32 v16, 16, v81
	v_and_b32_e32 v17, 0xffff0000, v81
	v_mul_f32_e32 v14, v130, v14
	v_mul_f32_e32 v15, v130, v15
	v_mul_f32_e32 v16, v130, v16
	v_mul_f32_e32 v17, v130, v17
	v_pk_mul_f32 v[14:15], v[14:15], v[62:63]
	v_pk_mul_f32 v[16:17], v[16:17], v[64:65]
	global_store_dwordx4 v6, v[14:17], s[12:13] offset:3072
	s_add_u32 vcc_lo, s32, 2048
	s_lshl_b32 vcc_lo, vcc_lo, 13
	s_add_u32 s12, s6, vcc_lo
	s_addc_u32 s13, s7, 0
	v_lshlrev_b32_e32 v10, 16, v82
	v_and_b32_e32 v11, 0xffff0000, v82
	v_lshlrev_b32_e32 v12, 16, v83
	v_and_b32_e32 v13, 0xffff0000, v83
	v_mul_f32_e32 v10, v131, v10
	v_mul_f32_e32 v11, v131, v11
	v_mul_f32_e32 v12, v131, v12
	v_mul_f32_e32 v13, v131, v13
	v_pk_mul_f32 v[10:11], v[10:11], v[34:35]
	v_pk_mul_f32 v[12:13], v[12:13], v[36:37]
	global_store_dwordx4 v4, v[10:13], s[12:13] offset:0
	v_lshlrev_b32_e32 v14, 16, v84
	v_and_b32_e32 v15, 0xffff0000, v84
	v_lshlrev_b32_e32 v16, 16, v85
	v_and_b32_e32 v17, 0xffff0000, v85
	v_mul_f32_e32 v14, v131, v14
	v_mul_f32_e32 v15, v131, v15
	v_mul_f32_e32 v16, v131, v16
	v_mul_f32_e32 v17, v131, v17
	v_pk_mul_f32 v[14:15], v[14:15], v[38:39]
	v_pk_mul_f32 v[16:17], v[16:17], v[40:41]
	global_store_dwordx4 v4, v[14:17], s[12:13] offset:1024
	v_lshlrev_b32_e32 v10, 16, v86
	v_and_b32_e32 v11, 0xffff0000, v86
	v_lshlrev_b32_e32 v12, 16, v87
	v_and_b32_e32 v13, 0xffff0000, v87
	v_mul_f32_e32 v10, v131, v10
	v_mul_f32_e32 v11, v131, v11
	v_mul_f32_e32 v12, v131, v12
	v_mul_f32_e32 v13, v131, v13
	v_pk_mul_f32 v[10:11], v[10:11], v[42:43]
	v_pk_mul_f32 v[12:13], v[12:13], v[44:45]
	global_store_dwordx4 v4, v[10:13], s[12:13] offset:2048
	v_lshlrev_b32_e32 v14, 16, v88
	v_and_b32_e32 v15, 0xffff0000, v88
	v_lshlrev_b32_e32 v16, 16, v89
	v_and_b32_e32 v17, 0xffff0000, v89
	v_mul_f32_e32 v14, v131, v14
	v_mul_f32_e32 v15, v131, v15
	v_mul_f32_e32 v16, v131, v16
	v_mul_f32_e32 v17, v131, v17
	v_pk_mul_f32 v[14:15], v[14:15], v[46:47]
	v_pk_mul_f32 v[16:17], v[16:17], v[48:49]
	global_store_dwordx4 v4, v[14:17], s[12:13] offset:3072
	v_lshlrev_b32_e32 v10, 16, v90
	v_and_b32_e32 v11, 0xffff0000, v90
	v_lshlrev_b32_e32 v12, 16, v91
	v_and_b32_e32 v13, 0xffff0000, v91
	v_mul_f32_e32 v10, v131, v10
	v_mul_f32_e32 v11, v131, v11
	v_mul_f32_e32 v12, v131, v12
	v_mul_f32_e32 v13, v131, v13
	v_pk_mul_f32 v[10:11], v[10:11], v[50:51]
	v_pk_mul_f32 v[12:13], v[12:13], v[52:53]
	global_store_dwordx4 v6, v[10:13], s[12:13] offset:0
	v_lshlrev_b32_e32 v14, 16, v92
	v_and_b32_e32 v15, 0xffff0000, v92
	v_lshlrev_b32_e32 v16, 16, v93
	v_and_b32_e32 v17, 0xffff0000, v93
	v_mul_f32_e32 v14, v131, v14
	v_mul_f32_e32 v15, v131, v15
	v_mul_f32_e32 v16, v131, v16
	v_mul_f32_e32 v17, v131, v17
	v_pk_mul_f32 v[14:15], v[14:15], v[54:55]
	v_pk_mul_f32 v[16:17], v[16:17], v[56:57]
	global_store_dwordx4 v6, v[14:17], s[12:13] offset:1024
	v_lshlrev_b32_e32 v10, 16, v94
	v_and_b32_e32 v11, 0xffff0000, v94
	v_lshlrev_b32_e32 v12, 16, v95
	v_and_b32_e32 v13, 0xffff0000, v95
	v_mul_f32_e32 v10, v131, v10
	v_mul_f32_e32 v11, v131, v11
	v_mul_f32_e32 v12, v131, v12
	v_mul_f32_e32 v13, v131, v13
	v_pk_mul_f32 v[10:11], v[10:11], v[58:59]
	v_pk_mul_f32 v[12:13], v[12:13], v[60:61]
	global_store_dwordx4 v6, v[10:13], s[12:13] offset:2048
	v_lshlrev_b32_e32 v14, 16, v96
	v_and_b32_e32 v15, 0xffff0000, v96
	v_lshlrev_b32_e32 v16, 16, v97
	v_and_b32_e32 v17, 0xffff0000, v97
	v_mul_f32_e32 v14, v131, v14
	v_mul_f32_e32 v15, v131, v15
	v_mul_f32_e32 v16, v131, v16
	v_mul_f32_e32 v17, v131, v17
	v_pk_mul_f32 v[14:15], v[14:15], v[62:63]
	v_pk_mul_f32 v[16:17], v[16:17], v[64:65]
	global_store_dwordx4 v6, v[14:17], s[12:13] offset:3072
	s_add_u32 vcc_lo, s32, 4096
	s_lshl_b32 vcc_lo, vcc_lo, 13
	s_add_u32 s12, s6, vcc_lo
	s_addc_u32 s13, s7, 0
	v_lshlrev_b32_e32 v10, 16, v98
	v_and_b32_e32 v11, 0xffff0000, v98
	v_lshlrev_b32_e32 v12, 16, v99
	v_and_b32_e32 v13, 0xffff0000, v99
	v_mul_f32_e32 v10, v132, v10
	v_mul_f32_e32 v11, v132, v11
	v_mul_f32_e32 v12, v132, v12
	v_mul_f32_e32 v13, v132, v13
	v_pk_mul_f32 v[10:11], v[10:11], v[34:35]
	v_pk_mul_f32 v[12:13], v[12:13], v[36:37]
	global_store_dwordx4 v4, v[10:13], s[12:13] offset:0
	v_lshlrev_b32_e32 v14, 16, v100
	v_and_b32_e32 v15, 0xffff0000, v100
	v_lshlrev_b32_e32 v16, 16, v101
	v_and_b32_e32 v17, 0xffff0000, v101
	v_mul_f32_e32 v14, v132, v14
	v_mul_f32_e32 v15, v132, v15
	v_mul_f32_e32 v16, v132, v16
	v_mul_f32_e32 v17, v132, v17
	v_pk_mul_f32 v[14:15], v[14:15], v[38:39]
	v_pk_mul_f32 v[16:17], v[16:17], v[40:41]
	global_store_dwordx4 v4, v[14:17], s[12:13] offset:1024
	v_lshlrev_b32_e32 v10, 16, v102
	v_and_b32_e32 v11, 0xffff0000, v102
	v_lshlrev_b32_e32 v12, 16, v103
	v_and_b32_e32 v13, 0xffff0000, v103
	v_mul_f32_e32 v10, v132, v10
	v_mul_f32_e32 v11, v132, v11
	v_mul_f32_e32 v12, v132, v12
	v_mul_f32_e32 v13, v132, v13
	v_pk_mul_f32 v[10:11], v[10:11], v[42:43]
	v_pk_mul_f32 v[12:13], v[12:13], v[44:45]
	global_store_dwordx4 v4, v[10:13], s[12:13] offset:2048
	v_lshlrev_b32_e32 v14, 16, v104
	v_and_b32_e32 v15, 0xffff0000, v104
	v_lshlrev_b32_e32 v16, 16, v105
	v_and_b32_e32 v17, 0xffff0000, v105
	v_mul_f32_e32 v14, v132, v14
	v_mul_f32_e32 v15, v132, v15
	v_mul_f32_e32 v16, v132, v16
	v_mul_f32_e32 v17, v132, v17
	v_pk_mul_f32 v[14:15], v[14:15], v[46:47]
	v_pk_mul_f32 v[16:17], v[16:17], v[48:49]
	global_store_dwordx4 v4, v[14:17], s[12:13] offset:3072
	v_lshlrev_b32_e32 v10, 16, v106
	v_and_b32_e32 v11, 0xffff0000, v106
	v_lshlrev_b32_e32 v12, 16, v107
	v_and_b32_e32 v13, 0xffff0000, v107
	v_mul_f32_e32 v10, v132, v10
	v_mul_f32_e32 v11, v132, v11
	v_mul_f32_e32 v12, v132, v12
	v_mul_f32_e32 v13, v132, v13
	v_pk_mul_f32 v[10:11], v[10:11], v[50:51]
	v_pk_mul_f32 v[12:13], v[12:13], v[52:53]
	global_store_dwordx4 v6, v[10:13], s[12:13] offset:0
	v_lshlrev_b32_e32 v14, 16, v108
	v_and_b32_e32 v15, 0xffff0000, v108
	v_lshlrev_b32_e32 v16, 16, v109
	v_and_b32_e32 v17, 0xffff0000, v109
	v_mul_f32_e32 v14, v132, v14
	v_mul_f32_e32 v15, v132, v15
	v_mul_f32_e32 v16, v132, v16
	v_mul_f32_e32 v17, v132, v17
	v_pk_mul_f32 v[14:15], v[14:15], v[54:55]
	v_pk_mul_f32 v[16:17], v[16:17], v[56:57]
	global_store_dwordx4 v6, v[14:17], s[12:13] offset:1024
	v_lshlrev_b32_e32 v10, 16, v110
	v_and_b32_e32 v11, 0xffff0000, v110
	v_lshlrev_b32_e32 v12, 16, v111
	v_and_b32_e32 v13, 0xffff0000, v111
	v_mul_f32_e32 v10, v132, v10
	v_mul_f32_e32 v11, v132, v11
	v_mul_f32_e32 v12, v132, v12
	v_mul_f32_e32 v13, v132, v13
	v_pk_mul_f32 v[10:11], v[10:11], v[58:59]
	v_pk_mul_f32 v[12:13], v[12:13], v[60:61]
	global_store_dwordx4 v6, v[10:13], s[12:13] offset:2048
	v_lshlrev_b32_e32 v14, 16, v112
	v_and_b32_e32 v15, 0xffff0000, v112
	v_lshlrev_b32_e32 v16, 16, v113
	v_and_b32_e32 v17, 0xffff0000, v113
	v_mul_f32_e32 v14, v132, v14
	v_mul_f32_e32 v15, v132, v15
	v_mul_f32_e32 v16, v132, v16
	v_mul_f32_e32 v17, v132, v17
	v_pk_mul_f32 v[14:15], v[14:15], v[62:63]
	v_pk_mul_f32 v[16:17], v[16:17], v[64:65]
	global_store_dwordx4 v6, v[14:17], s[12:13] offset:3072
	s_add_u32 vcc_lo, s32, 6144
	s_lshl_b32 vcc_lo, vcc_lo, 13
	s_add_u32 s12, s6, vcc_lo
	s_addc_u32 s13, s7, 0
	v_lshlrev_b32_e32 v10, 16, v114
	v_and_b32_e32 v11, 0xffff0000, v114
	v_lshlrev_b32_e32 v12, 16, v115
	v_and_b32_e32 v13, 0xffff0000, v115
	v_mul_f32_e32 v10, v133, v10
	v_mul_f32_e32 v11, v133, v11
	v_mul_f32_e32 v12, v133, v12
	v_mul_f32_e32 v13, v133, v13
	v_pk_mul_f32 v[10:11], v[10:11], v[34:35]
	v_pk_mul_f32 v[12:13], v[12:13], v[36:37]
	global_store_dwordx4 v4, v[10:13], s[12:13] offset:0
	v_lshlrev_b32_e32 v14, 16, v116
	v_and_b32_e32 v15, 0xffff0000, v116
	v_lshlrev_b32_e32 v16, 16, v117
	v_and_b32_e32 v17, 0xffff0000, v117
	v_mul_f32_e32 v14, v133, v14
	v_mul_f32_e32 v15, v133, v15
	v_mul_f32_e32 v16, v133, v16
	v_mul_f32_e32 v17, v133, v17
	v_pk_mul_f32 v[14:15], v[14:15], v[38:39]
	v_pk_mul_f32 v[16:17], v[16:17], v[40:41]
	global_store_dwordx4 v4, v[14:17], s[12:13] offset:1024
	v_lshlrev_b32_e32 v10, 16, v118
	v_and_b32_e32 v11, 0xffff0000, v118
	v_lshlrev_b32_e32 v12, 16, v119
	v_and_b32_e32 v13, 0xffff0000, v119
	v_mul_f32_e32 v10, v133, v10
	v_mul_f32_e32 v11, v133, v11
	v_mul_f32_e32 v12, v133, v12
	v_mul_f32_e32 v13, v133, v13
	v_pk_mul_f32 v[10:11], v[10:11], v[42:43]
	v_pk_mul_f32 v[12:13], v[12:13], v[44:45]
	global_store_dwordx4 v4, v[10:13], s[12:13] offset:2048
	v_lshlrev_b32_e32 v14, 16, v120
	v_and_b32_e32 v15, 0xffff0000, v120
	v_lshlrev_b32_e32 v16, 16, v121
	v_and_b32_e32 v17, 0xffff0000, v121
	v_mul_f32_e32 v14, v133, v14
	v_mul_f32_e32 v15, v133, v15
	v_mul_f32_e32 v16, v133, v16
	v_mul_f32_e32 v17, v133, v17
	v_pk_mul_f32 v[14:15], v[14:15], v[46:47]
	v_pk_mul_f32 v[16:17], v[16:17], v[48:49]
	global_store_dwordx4 v4, v[14:17], s[12:13] offset:3072
	v_lshlrev_b32_e32 v10, 16, v122
	v_and_b32_e32 v11, 0xffff0000, v122
	v_lshlrev_b32_e32 v12, 16, v123
	v_and_b32_e32 v13, 0xffff0000, v123
	v_mul_f32_e32 v10, v133, v10
	v_mul_f32_e32 v11, v133, v11
	v_mul_f32_e32 v12, v133, v12
	v_mul_f32_e32 v13, v133, v13
	v_pk_mul_f32 v[10:11], v[10:11], v[50:51]
	v_pk_mul_f32 v[12:13], v[12:13], v[52:53]
	global_store_dwordx4 v6, v[10:13], s[12:13] offset:0
	v_lshlrev_b32_e32 v14, 16, v124
	v_and_b32_e32 v15, 0xffff0000, v124
	v_lshlrev_b32_e32 v16, 16, v125
	v_and_b32_e32 v17, 0xffff0000, v125
	v_mul_f32_e32 v14, v133, v14
	v_mul_f32_e32 v15, v133, v15
	v_mul_f32_e32 v16, v133, v16
	v_mul_f32_e32 v17, v133, v17
	v_pk_mul_f32 v[14:15], v[14:15], v[54:55]
	v_pk_mul_f32 v[16:17], v[16:17], v[56:57]
	global_store_dwordx4 v6, v[14:17], s[12:13] offset:1024
	v_lshlrev_b32_e32 v10, 16, v126
	v_and_b32_e32 v11, 0xffff0000, v126
	v_lshlrev_b32_e32 v12, 16, v127
	v_and_b32_e32 v13, 0xffff0000, v127
	v_mul_f32_e32 v10, v133, v10
	v_mul_f32_e32 v11, v133, v11
	v_mul_f32_e32 v12, v133, v12
	v_mul_f32_e32 v13, v133, v13
	v_pk_mul_f32 v[10:11], v[10:11], v[58:59]
	v_pk_mul_f32 v[12:13], v[12:13], v[60:61]
	global_store_dwordx4 v6, v[10:13], s[12:13] offset:2048
	v_lshlrev_b32_e32 v14, 16, v128
	v_and_b32_e32 v15, 0xffff0000, v128
	v_lshlrev_b32_e32 v16, 16, v129
	v_and_b32_e32 v17, 0xffff0000, v129
	v_mul_f32_e32 v14, v133, v14
	v_mul_f32_e32 v15, v133, v15
	v_mul_f32_e32 v16, v133, v16
	v_mul_f32_e32 v17, v133, v17
	v_pk_mul_f32 v[14:15], v[14:15], v[62:63]
	v_pk_mul_f32 v[16:17], v[16:17], v[64:65]
	global_store_dwordx4 v6, v[14:17], s[12:13] offset:3072
	s_cmp_lt_u32 s32, 0x100
	s_cbranch_scc0 .Lfn_s4skip
	s_add_u32 vcc_lo, s32, 8192
	s_lshl_b32 vcc_lo, vcc_lo, 13
	s_add_u32 s12, s6, vcc_lo
	s_addc_u32 s13, s7, 0
	v_lshlrev_b32_e32 v10, 16, v142
	v_and_b32_e32 v11, 0xffff0000, v142
	v_lshlrev_b32_e32 v12, 16, v143
	v_and_b32_e32 v13, 0xffff0000, v143
	v_mul_f32_e32 v10, v134, v10
	v_mul_f32_e32 v11, v134, v11
	v_mul_f32_e32 v12, v134, v12
	v_mul_f32_e32 v13, v134, v13
	v_pk_mul_f32 v[10:11], v[10:11], v[34:35]
	v_pk_mul_f32 v[12:13], v[12:13], v[36:37]
	global_store_dwordx4 v4, v[10:13], s[12:13] offset:0
	v_lshlrev_b32_e32 v14, 16, v144
	v_and_b32_e32 v15, 0xffff0000, v144
	v_lshlrev_b32_e32 v16, 16, v145
	v_and_b32_e32 v17, 0xffff0000, v145
	v_mul_f32_e32 v14, v134, v14
	v_mul_f32_e32 v15, v134, v15
	v_mul_f32_e32 v16, v134, v16
	v_mul_f32_e32 v17, v134, v17
	v_pk_mul_f32 v[14:15], v[14:15], v[38:39]
	v_pk_mul_f32 v[16:17], v[16:17], v[40:41]
	global_store_dwordx4 v4, v[14:17], s[12:13] offset:1024
	v_lshlrev_b32_e32 v10, 16, v146
	v_and_b32_e32 v11, 0xffff0000, v146
	v_lshlrev_b32_e32 v12, 16, v147
	v_and_b32_e32 v13, 0xffff0000, v147
	v_mul_f32_e32 v10, v134, v10
	v_mul_f32_e32 v11, v134, v11
	v_mul_f32_e32 v12, v134, v12
	v_mul_f32_e32 v13, v134, v13
	v_pk_mul_f32 v[10:11], v[10:11], v[42:43]
	v_pk_mul_f32 v[12:13], v[12:13], v[44:45]
	global_store_dwordx4 v4, v[10:13], s[12:13] offset:2048
	v_lshlrev_b32_e32 v14, 16, v148
	v_and_b32_e32 v15, 0xffff0000, v148
	v_lshlrev_b32_e32 v16, 16, v149
	v_and_b32_e32 v17, 0xffff0000, v149
	v_mul_f32_e32 v14, v134, v14
	v_mul_f32_e32 v15, v134, v15
	v_mul_f32_e32 v16, v134, v16
	v_mul_f32_e32 v17, v134, v17
	v_pk_mul_f32 v[14:15], v[14:15], v[46:47]
	v_pk_mul_f32 v[16:17], v[16:17], v[48:49]
	global_store_dwordx4 v4, v[14:17], s[12:13] offset:3072
	v_lshlrev_b32_e32 v10, 16, v150
	v_and_b32_e32 v11, 0xffff0000, v150
	v_lshlrev_b32_e32 v12, 16, v151
	v_and_b32_e32 v13, 0xffff0000, v151
	v_mul_f32_e32 v10, v134, v10
	v_mul_f32_e32 v11, v134, v11
	v_mul_f32_e32 v12, v134, v12
	v_mul_f32_e32 v13, v134, v13
	v_pk_mul_f32 v[10:11], v[10:11], v[50:51]
	v_pk_mul_f32 v[12:13], v[12:13], v[52:53]
	global_store_dwordx4 v6, v[10:13], s[12:13] offset:0
	v_lshlrev_b32_e32 v14, 16, v152
	v_and_b32_e32 v15, 0xffff0000, v152
	v_lshlrev_b32_e32 v16, 16, v153
	v_and_b32_e32 v17, 0xffff0000, v153
	v_mul_f32_e32 v14, v134, v14
	v_mul_f32_e32 v15, v134, v15
	v_mul_f32_e32 v16, v134, v16
	v_mul_f32_e32 v17, v134, v17
	v_pk_mul_f32 v[14:15], v[14:15], v[54:55]
	v_pk_mul_f32 v[16:17], v[16:17], v[56:57]
	global_store_dwordx4 v6, v[14:17], s[12:13] offset:1024
	v_lshlrev_b32_e32 v10, 16, v154
	v_and_b32_e32 v11, 0xffff0000, v154
	v_lshlrev_b32_e32 v12, 16, v155
	v_and_b32_e32 v13, 0xffff0000, v155
	v_mul_f32_e32 v10, v134, v10
	v_mul_f32_e32 v11, v134, v11
	v_mul_f32_e32 v12, v134, v12
	v_mul_f32_e32 v13, v134, v13
	v_pk_mul_f32 v[10:11], v[10:11], v[58:59]
	v_pk_mul_f32 v[12:13], v[12:13], v[60:61]
	global_store_dwordx4 v6, v[10:13], s[12:13] offset:2048
	v_lshlrev_b32_e32 v14, 16, v156
	v_and_b32_e32 v15, 0xffff0000, v156
	v_lshlrev_b32_e32 v16, 16, v157
	v_and_b32_e32 v17, 0xffff0000, v157
	v_mul_f32_e32 v14, v134, v14
	v_mul_f32_e32 v15, v134, v15
	v_mul_f32_e32 v16, v134, v16
	v_mul_f32_e32 v17, v134, v17
	v_pk_mul_f32 v[14:15], v[14:15], v[62:63]
	v_pk_mul_f32 v[16:17], v[16:17], v[64:65]
	global_store_dwordx4 v6, v[14:17], s[12:13] offset:3072
.Lfn_s4skip:
	s_mov_b64 s[4:5], exec

.LBB0_396:
	s_sub_u32 vcc_lo, s37, s66
	s_cmp_ge_u32 vcc_lo, 64
	s_cbranch_scc0 .Lsg_single
	v_lshl_add_u64 v[60:61], v[34:35], 0, s[6:7]
	v_lshl_add_u64 v[62:63], v[36:37], 0, s[6:7]
	v_lshl_add_u64 v[64:65], v[38:39], 0, s[6:7]
	v_lshl_add_u64 v[66:67], v[44:45], 0, s[6:7]
	v_lshl_add_u64 v[68:69], v[40:41], 0, s[6:7]
	v_lshl_add_u64 v[70:71], v[42:43], 0, s[6:7]
	global_load_dwordx4 v[50:53], v[60:61], off
	global_load_dwordx4 v[54:57], v[62:63], off
	global_load_dwordx4 v[46:49], v[64:65], off
	global_load_dwordx4 v[72:75], v[66:67], off
	global_load_dwordx4 v[76:79], v[68:69], off
	global_load_dwordx4 v[80:83], v[70:71], off
	s_add_u32 s6, s6, 64
	s_addc_u32 s7, s7, 0
	v_lshl_add_u64 v[60:61], v[34:35], 0, s[6:7]
	v_lshl_add_u64 v[62:63], v[36:37], 0, s[6:7]
	v_lshl_add_u64 v[64:65], v[38:39], 0, s[6:7]
	v_lshl_add_u64 v[66:67], v[44:45], 0, s[6:7]
	v_lshl_add_u64 v[68:69], v[40:41], 0, s[6:7]
	v_lshl_add_u64 v[70:71], v[42:43], 0, s[6:7]
	global_load_dwordx4 v[84:87], v[60:61], off
	global_load_dwordx4 v[88:91], v[62:63], off
	global_load_dwordx4 v[92:95], v[64:65], off
	global_load_dwordx4 v[96:99], v[66:67], off
	global_load_dwordx4 v[100:103], v[68:69], off
	global_load_dwordx4 v[104:107], v[70:71], off
	s_add_u32 s6, s6, 64
	s_addc_u32 s7, s7, 0
	s_add_i32 s66, s66, 64
	s_waitcnt vmcnt(9)
	v_mfma_f32_16x16x32_bf16 v[30:33], v[46:49], v[50:53], v[30:33]
	v_mfma_f32_16x16x32_bf16 v[6:9], v[46:49], v[54:57], v[6:9]
	s_waitcnt vmcnt(8)
	v_mfma_f32_16x16x32_bf16 v[26:29], v[72:75], v[50:53], v[26:29]
	v_mfma_f32_16x16x32_bf16 v[10:13], v[72:75], v[54:57], v[10:13]
	s_waitcnt vmcnt(7)
	v_mfma_f32_16x16x32_bf16 v[14:17], v[76:79], v[50:53], v[14:17]
	v_mfma_f32_16x16x32_bf16 v[22:25], v[76:79], v[54:57], v[22:25]
	s_waitcnt vmcnt(6)
	v_mfma_f32_16x16x32_bf16 v[2:5], v[80:83], v[50:53], v[2:5]
	v_mfma_f32_16x16x32_bf16 v[18:21], v[80:83], v[54:57], v[18:21]
	s_waitcnt vmcnt(3)
	v_mfma_f32_16x16x32_bf16 v[30:33], v[92:95], v[84:87], v[30:33]
	v_mfma_f32_16x16x32_bf16 v[6:9], v[92:95], v[88:91], v[6:9]
	s_waitcnt vmcnt(2)
	v_mfma_f32_16x16x32_bf16 v[26:29], v[96:99], v[84:87], v[26:29]
	v_mfma_f32_16x16x32_bf16 v[10:13], v[96:99], v[88:91], v[10:13]
	s_waitcnt vmcnt(1)
	v_mfma_f32_16x16x32_bf16 v[14:17], v[100:103], v[84:87], v[14:17]
	v_mfma_f32_16x16x32_bf16 v[22:25], v[100:103], v[88:91], v[22:25]
	s_waitcnt vmcnt(0)
	v_mfma_f32_16x16x32_bf16 v[2:5], v[104:107], v[84:87], v[2:5]
	v_mfma_f32_16x16x32_bf16 v[18:21], v[104:107], v[88:91], v[18:21]
	s_cmp_lt_u32 s66, s37
	s_cbranch_scc1 .LBB0_396
	s_branch .LBB0_397
.Lsg_single:
	v_lshl_add_u64 v[60:61], v[34:35], 0, s[6:7]
	v_lshl_add_u64 v[62:63], v[36:37], 0, s[6:7]
	v_lshl_add_u64 v[64:65], v[38:39], 0, s[6:7]
	v_lshl_add_u64 v[66:67], v[44:45], 0, s[6:7]
	v_lshl_add_u64 v[68:69], v[40:41], 0, s[6:7]
	v_lshl_add_u64 v[70:71], v[42:43], 0, s[6:7]
	global_load_dwordx4 v[50:53], v[60:61], off
	global_load_dwordx4 v[54:57], v[62:63], off
	global_load_dwordx4 v[46:49], v[64:65], off
	global_load_dwordx4 v[72:75], v[66:67], off
	global_load_dwordx4 v[76:79], v[68:69], off
	global_load_dwordx4 v[80:83], v[70:71], off
	s_add_u32 s6, s6, 64
	s_addc_u32 s7, s7, 0
	s_add_i32 s66, s66, 32
	s_waitcnt vmcnt(3)
	v_mfma_f32_16x16x32_bf16 v[30:33], v[46:49], v[50:53], v[30:33]
	v_mfma_f32_16x16x32_bf16 v[6:9], v[46:49], v[54:57], v[6:9]
	s_waitcnt vmcnt(2)
	v_mfma_f32_16x16x32_bf16 v[26:29], v[72:75], v[50:53], v[26:29]
	v_mfma_f32_16x16x32_bf16 v[10:13], v[72:75], v[54:57], v[10:13]
	s_waitcnt vmcnt(1)
	v_mfma_f32_16x16x32_bf16 v[14:17], v[76:79], v[50:53], v[14:17]
	v_mfma_f32_16x16x32_bf16 v[22:25], v[76:79], v[54:57], v[22:25]
	s_waitcnt vmcnt(0)
	v_mfma_f32_16x16x32_bf16 v[2:5], v[80:83], v[50:53], v[2:5]
	v_mfma_f32_16x16x32_bf16 v[18:21], v[80:83], v[54:57], v[18:21]
	s_cmp_lt_u32 s66, s37
	s_cbranch_scc1 .LBB0_396
